# final RMSNorm: lanes own float4 pieces 1KB apart so every load/store instruction covers 1KB contiguous (was half of each 32B)
# speedup vs baseline: 1.0044x; 1.0003x over previous
; __device__ __forceinline__ int tid_fresh() { int t = threadIdx.x; asm volatile("" : "+v"(t)); return t; }
; __device__ __forceinline__ int bid_fresh() { int b = blockIdx.x; asm volatile("" : "+s"(b)); return b; }
; __device__ __forceinline__ int gdim_fresh() { int g = gridDim.x; asm volatile("" : "+s"(g)); return g; }
; template <bool FINAL>
; __device__ __forceinline__ void norm_phase(const float* src, const float* gain, bf16_t* dst, float* fdst) {
;     const int tid = tid_fresh(), wid = tid >> 6, lane = tid & 63;
;     const int NW = gdim_fresh() * 8;
;     for (int row = bid_fresh() * 8 + wid; row < SEQ; row += NW) {
;         const float* xr = src + (size_t)row * DM + lane * 8;
;         f32x4 v[8];
; #pragma unroll
;         for (int i = 0; i < 4; ++i) { v[2 * i] = *(const f32x4*)(xr + 512 * i); v[2 * i + 1] = *(const f32x4*)(xr + 512 * i + 4); }
;         float ss = 0.f;
; #pragma unroll
;         for (int i = 0; i < 8; ++i) ss += (v[i][0] * v[i][0] + v[i][1] * v[i][1]) + (v[i][2] * v[i][2] + v[i][3] * v[i][3]);
; #pragma unroll
;         for (int o = 1; o < 64; o <<= 1) ss += __shfl_xor(ss, o);
;         const float rstd = 1.0f / sqrtf(ss * (1.0f / DM) + RMS_EPS);
.LBB0_685:
	s_movk_i32 s0, 0x4000
	v_ashrrev_i32_e32 v0, 6, v166
	v_lshl_add_u32 v32, s83, 3, v0
	v_cmp_gt_i32_e32 vcc, s0, v32
	s_and_saveexec_b64 s[0:1], vcc
	s_cbranch_execz .LBB0_688
	s_load_dwordx4 s[0:3], s[96:97], 0x80
	v_and_b32_e32 v0, 64, v167
	v_add_u32_e32 v2, 64, v0
	v_lshlrev_b32_e32 v0, 4, v166
	v_and_b32_e32 v0, 0x3f0, v0
	v_mov_b32_e32 v1, 0
	s_waitcnt lgkmcnt(0)
	v_lshl_add_u64 v[34:35], s[0:1], 0, v[0:1]
	v_xor_b32_e32 v0, 1, v167
	v_cmp_lt_i32_e32 vcc, v0, v2
	v_ashrrev_i32_e32 v33, 31, v32
	s_lshl_b32 s4, s91, 3
	v_cndmask_b32_e32 v0, v167, v0, vcc
	v_lshlrev_b32_e32 v42, 2, v0
	v_xor_b32_e32 v0, 2, v167
	v_cmp_lt_i32_e32 vcc, v0, v2
	s_mov_b64 s[0:1], 0x1000
	s_mov_b64 s[6:7], 0x1800
	v_cndmask_b32_e32 v0, v167, v0, vcc
	v_lshlrev_b32_e32 v43, 2, v0
	v_xor_b32_e32 v0, 4, v167
	v_cmp_lt_i32_e32 vcc, v0, v2
	s_ashr_i32 s5, s4, 31
	v_lshl_add_u64 v[36:37], v[34:35], 0, s[0:1]
	v_cndmask_b32_e32 v0, v167, v0, vcc
	v_lshlrev_b32_e32 v44, 2, v0
	v_xor_b32_e32 v0, 8, v167
	v_cmp_lt_i32_e32 vcc, v0, v2
	v_lshl_add_u64 v[38:39], v[34:35], 0, s[6:7]
	s_mov_b64 s[6:7], 0
	v_cndmask_b32_e32 v0, v167, v0, vcc
	v_lshlrev_b32_e32 v45, 2, v0
	v_xor_b32_e32 v0, 16, v167
	v_cmp_lt_i32_e32 vcc, v0, v2
	v_mov_b32_e32 v48, 0x260
	s_movk_i32 s8, 0x3fff
	v_cndmask_b32_e32 v0, v167, v0, vcc
	v_lshlrev_b32_e32 v46, 2, v0
	v_xor_b32_e32 v0, 32, v167
	v_cmp_lt_i32_e32 vcc, v0, v2
	v_and_b32_e32 v2, 63, v166
	s_nop 0
	v_cndmask_b32_e32 v0, v167, v0, vcc
	v_lshlrev_b32_e32 v47, 2, v0
	v_lshlrev_b64 v[0:1], 13, v[32:33]
	v_lshl_or_b32 v0, v2, 4, v0
	v_lshl_add_u64 v[0:1], s[2:3], 0, v[0:1]
	v_lshl_add_u64 v[40:41], v[0:1], 0, s[0:1]
	s_lshl_b64 s[2:3], s[4:5], 13
	v_mov_b32_e32 v33, 0x358637bd
	s_mov_b32 s5, 0xf800000
.LBB0_687:
	global_load_dwordx4 v[28:31], v[40:41], off offset:-4096
	global_load_dwordx4 v[24:27], v[40:41], off offset:-3072
	global_load_dwordx4 v[20:23], v[40:41], off offset:-2048
	global_load_dwordx4 v[8:11], v[40:41], off offset:1024
	global_load_dwordx4 v[12:15], v[40:41], off
	global_load_dwordx4 v[16:19], v[40:41], off offset:-1024
	global_load_dwordx4 v[0:3], v[40:41], off offset:3072
	global_load_dwordx4 v[4:7], v[40:41], off offset:2048
	global_load_dwordx4 v[50:53], v[34:35], off offset:1024
	global_load_dwordx4 v[54:57], v[34:35], off
	v_add_u32_e32 v32, s4, v32
	s_waitcnt vmcnt(9)
	v_mov_b32_e32 v60, v29
	s_waitcnt vmcnt(8)
	v_mov_b32_e32 v61, v25
	v_mov_b32_e32 v64, v31
	v_mov_b32_e32 v65, v27
	v_mov_b32_e32 v58, v28
	v_mov_b32_e32 v59, v24
	v_mov_b32_e32 v62, v30
	v_mov_b32_e32 v63, v26
	s_waitcnt vmcnt(7)
	v_pk_mul_f32 v[66:67], v[22:23], v[22:23]
	v_pk_mul_f32 v[68:69], v[20:21], v[20:21]
	v_pk_mul_f32 v[60:61], v[60:61], v[60:61]
	v_pk_mul_f32 v[64:65], v[64:65], v[64:65]
	v_pk_mov_b32 v[82:83], v[68:69], v[66:67] op_sel:[1,0]
	v_mov_b32_e32 v69, v67
	v_pk_fma_f32 v[58:59], v[58:59], v[58:59], v[60:61]
	v_pk_fma_f32 v[60:61], v[62:63], v[62:63], v[64:65]
	s_waitcnt vmcnt(6)
	v_pk_mul_f32 v[70:71], v[10:11], v[10:11]
	v_pk_mul_f32 v[72:73], v[8:9], v[8:9]
	s_waitcnt vmcnt(4)
	v_mul_f32_e32 v74, v17, v17
	v_mul_f32_e32 v76, v19, v19
	v_pk_add_f32 v[62:63], v[82:83], v[68:69]
	v_pk_add_f32 v[58:59], v[58:59], v[60:61]
	v_mul_f32_e32 v49, v12, v12
	v_mul_f32_e32 v81, v13, v13
	v_mul_f32_e32 v84, v14, v14
	v_mul_f32_e32 v85, v15, v15
	v_pk_mov_b32 v[66:67], v[72:73], v[70:71] op_sel:[1,0]
	v_mov_b32_e32 v73, v71
	v_pk_fma_f32 v[70:71], v[16:17], v[16:17], v[74:75] op_sel_hi:[1,1,0]
	v_pk_fma_f32 v[74:75], v[18:19], v[18:19], v[76:77] op_sel_hi:[1,1,0]
	v_pk_add_f32 v[60:61], v[62:63], v[62:63] op_sel:[0,1] op_sel_hi:[1,0]
	v_pk_add_f32 v[58:59], v[58:59], v[58:59] op_sel:[0,1] op_sel_hi:[1,0]
	v_mov_b32_e32 v71, v84
	v_mov_b32_e32 v75, v85
	v_mov_b32_e32 v61, v81
	v_mov_b32_e32 v59, v49
	v_pk_add_f32 v[62:63], v[70:71], v[74:75]
	v_pk_add_f32 v[58:59], v[58:59], v[60:61]
	s_waitcnt vmcnt(2)
	v_mul_f32_e32 v78, v5, v5
	v_mul_f32_e32 v80, v7, v7
	v_pk_add_f32 v[64:65], v[66:67], v[72:73]
	v_pk_add_f32 v[58:59], v[58:59], v[62:63]
	v_mul_f32_e32 v86, v0, v0
	v_mul_f32_e32 v87, v2, v2
	v_mul_f32_e32 v88, v3, v3
	v_mul_f32_e32 v89, v1, v1
	v_pk_fma_f32 v[76:77], v[4:5], v[4:5], v[78:79] op_sel_hi:[1,1,0]
	v_pk_fma_f32 v[78:79], v[6:7], v[6:7], v[80:81] op_sel_hi:[1,1,0]
	v_pk_add_f32 v[64:65], v[64:65], v[64:65] op_sel:[0,1] op_sel_hi:[1,0]
	v_pk_add_f32 v[58:59], v[58:59], v[58:59] op_sel:[0,1] op_sel_hi:[1,0]
	v_mov_b32_e32 v77, v87
	v_mov_b32_e32 v79, v88
	v_mov_b32_e32 v65, v89
	v_mov_b32_e32 v59, v86
	v_pk_add_f32 v[66:67], v[76:77], v[78:79]
	v_pk_add_f32 v[58:59], v[58:59], v[64:65]
	s_nop 0
	v_pk_add_f32 v[58:59], v[58:59], v[66:67]
	s_nop 0
	v_add_f32_e32 v49, v58, v59
	ds_bpermute_b32 v58, v42, v49
	s_waitcnt lgkmcnt(0)
; __device__ __forceinline__ unsigned cvt_pk_bf16(float lo, float hi) { unsigned r; asm volatile("v_cvt_pk_bf16_f32 %0, %1, %2" : "=v"(r) : "v"(lo), "v"(hi)); return r; }
; template <bool FINAL>
; __device__ __forceinline__ void norm_phase(const float* src, const float* gain, bf16_t* dst, float* fdst) {
;     ...
; #pragma unroll
;         for (int o = 1; o < 64; o <<= 1) ss += __shfl_xor(ss, o);
;         const float rstd = 1.0f / sqrtf(ss * (1.0f / DM) + RMS_EPS);
; #pragma unroll
;         for (int i = 0; i < 4; ++i) {
;             const f32x4 g0 = *(const f32x4*)(gain + lane * 8 + 512 * i), g1 = *(const f32x4*)(gain + lane * 8 + 512 * i + 4);
;             const f32x4 y0 = v[2 * i] * rstd * g0, y1 = v[2 * i + 1] * rstd * g1;
;             if (FINAL) { float* o = fdst + (size_t)row * DM + lane * 8 + 512 * i; *(f32x4*)o = y0; *(f32x4*)(o + 4) = y1; }
;             else { u32x4 w; w.x = cvt_pk_bf16(y0[0], y0[1]); w.y = cvt_pk_bf16(y0[2], y0[3]); w.z = cvt_pk_bf16(y1[0], y1[1]); w.w = cvt_pk_bf16(y1[2], y1[3]);
;                 *(u32x4*)(dst + (size_t)row * DM + lane * 8 + 512 * i) = w; }
;         }
	v_add_f32_e32 v49, v49, v58
	ds_bpermute_b32 v58, v43, v49
	s_waitcnt lgkmcnt(0)
	v_add_f32_e32 v49, v49, v58
	ds_bpermute_b32 v58, v44, v49
	s_waitcnt lgkmcnt(0)
	v_add_f32_e32 v49, v49, v58
	ds_bpermute_b32 v58, v45, v49
	s_waitcnt lgkmcnt(0)
	v_add_f32_e32 v49, v49, v58
	ds_bpermute_b32 v58, v46, v49
	s_waitcnt lgkmcnt(0)
	v_add_f32_e32 v49, v49, v58
	ds_bpermute_b32 v58, v47, v49
	s_waitcnt lgkmcnt(0)
	v_add_f32_e32 v49, v49, v58
	v_fmamk_f32 v49, v49, 0x3a000000, v33
	v_mul_f32_e32 v58, 0x4f800000, v49
	v_cmp_gt_f32_e32 vcc, s5, v49
	s_nop 1
	v_cndmask_b32_e32 v49, v49, v58, vcc
	v_sqrt_f32_e32 v58, v49
	s_nop 0
	v_add_u32_e32 v59, -1, v58
	v_add_u32_e32 v60, 1, v58
	v_fma_f32 v61, -v59, v58, v49
	v_fma_f32 v62, -v60, v58, v49
	v_cmp_ge_f32_e64 s[0:1], 0, v61
	s_nop 1
	v_cndmask_b32_e64 v58, v58, v59, s[0:1]
	v_cmp_lt_f32_e64 s[0:1], 0, v62
	s_nop 1
	v_cndmask_b32_e64 v58, v58, v60, s[0:1]
	v_mul_f32_e32 v59, 0x37800000, v58
	v_cndmask_b32_e32 v58, v58, v59, vcc
	v_cmp_class_f32_e32 vcc, v49, v48
	s_nop 1
	v_cndmask_b32_e32 v49, v58, v49, vcc
	v_div_scale_f32 v58, s[0:1], v49, v49, 1.0
	v_rcp_f32_e32 v59, v58
	v_div_scale_f32 v60, vcc, 1.0, v49, 1.0
	v_fma_f32 v61, -v58, v59, 1.0
	v_fmac_f32_e32 v59, v61, v59
	v_mul_f32_e32 v61, v60, v59
	v_fma_f32 v62, -v58, v61, v60
	v_fmac_f32_e32 v61, v62, v59
	v_fma_f32 v58, -v58, v61, v60
	v_div_fmas_f32 v58, v58, v59, v61
	v_div_fixup_f32 v58, v58, v49, 1.0
	v_pk_mul_f32 v[28:29], v[28:29], v[58:59] op_sel_hi:[1,0]
	v_pk_mul_f32 v[30:31], v[30:31], v[58:59] op_sel_hi:[1,0]
	v_pk_mul_f32 v[60:61], v[24:25], v[58:59] op_sel_hi:[1,0]
	v_pk_mul_f32 v[62:63], v[26:27], v[58:59] op_sel_hi:[1,0]
	s_waitcnt vmcnt(0)
	v_pk_mul_f32 v[26:27], v[56:57], v[30:31]
	v_pk_mul_f32 v[24:25], v[54:55], v[28:29]
	v_pk_mul_f32 v[30:31], v[52:53], v[62:63]
	v_pk_mul_f32 v[28:29], v[50:51], v[60:61]
	global_store_dwordx4 v[40:41], v[24:27], off offset:-4096
	global_store_dwordx4 v[40:41], v[28:31], off offset:-3072
	global_load_dwordx4 v[24:27], v[34:35], off offset:2048
	s_nop 0
	global_load_dwordx4 v[28:31], v[34:35], off offset:3072
	v_pk_mul_f32 v[22:23], v[22:23], v[58:59] op_sel_hi:[1,0]
	v_pk_mul_f32 v[20:21], v[20:21], v[58:59] op_sel_hi:[1,0]
	v_pk_mul_f32 v[50:51], v[18:19], v[58:59] op_sel_hi:[1,0]
	v_pk_mul_f32 v[52:53], v[16:17], v[58:59] op_sel_hi:[1,0]
	v_pk_mul_f32 v[14:15], v[14:15], v[58:59] op_sel_hi:[1,0]
	v_pk_mul_f32 v[12:13], v[12:13], v[58:59] op_sel_hi:[1,0]
	v_pk_mul_f32 v[6:7], v[6:7], v[58:59] op_sel_hi:[1,0]
	v_pk_mul_f32 v[4:5], v[4:5], v[58:59] op_sel_hi:[1,0]
	v_cmp_lt_i32_e32 vcc, s8, v32
	s_or_b64 s[6:7], vcc, s[6:7]
	s_waitcnt vmcnt(1)
	v_pk_mul_f32 v[16:17], v[24:25], v[20:21]
	v_pk_mul_f32 v[18:19], v[26:27], v[22:23]
	s_waitcnt vmcnt(0)
	v_pk_mul_f32 v[20:21], v[28:29], v[52:53]
	v_pk_mul_f32 v[22:23], v[30:31], v[50:51]
	global_store_dwordx4 v[40:41], v[16:19], off offset:-2048
	global_store_dwordx4 v[40:41], v[20:23], off offset:-1024
	global_load_dwordx4 v[16:19], v[36:37], off
	s_nop 0
	global_load_dwordx4 v[20:23], v[36:37], off offset:1024
	v_pk_mul_f32 v[24:25], v[10:11], v[58:59] op_sel_hi:[1,0]
	v_pk_mul_f32 v[26:27], v[8:9], v[58:59] op_sel_hi:[1,0]
	s_waitcnt vmcnt(1)
	v_pk_mul_f32 v[8:9], v[16:17], v[12:13]
	v_pk_mul_f32 v[10:11], v[18:19], v[14:15]
	s_waitcnt vmcnt(0)
	v_pk_mul_f32 v[12:13], v[20:21], v[26:27]
	v_pk_mul_f32 v[14:15], v[22:23], v[24:25]
	global_store_dwordx4 v[40:41], v[8:11], off
	global_store_dwordx4 v[40:41], v[12:15], off offset:1024
	global_load_dwordx4 v[8:11], v[38:39], off
	s_nop 0
	global_load_dwordx4 v[12:15], v[38:39], off offset:1024
	v_pk_mul_f32 v[16:17], v[2:3], v[58:59] op_sel_hi:[1,0]
	v_pk_mul_f32 v[18:19], v[0:1], v[58:59] op_sel_hi:[1,0]
	s_waitcnt vmcnt(1)
	v_pk_mul_f32 v[0:1], v[4:5], v[8:9]
	v_pk_mul_f32 v[2:3], v[6:7], v[10:11]
	s_waitcnt vmcnt(0)
	v_pk_mul_f32 v[4:5], v[18:19], v[12:13]
	v_pk_mul_f32 v[6:7], v[16:17], v[14:15]
	global_store_dwordx4 v[40:41], v[0:3], off offset:2048
	global_store_dwordx4 v[40:41], v[4:7], off offset:3072
	v_lshl_add_u64 v[40:41], v[40:41], 0, s[2:3]
	s_andn2_b64 exec, exec, s[6:7]
	s_cbranch_execnz .LBB0_687
